# NSA priority raise moved from waves 0-3 to waves 4-7 (same code otherwise as conv83)
# speedup vs baseline: 1.0003x; 1.0003x over previous
; #define LAS __attribute__((address_space(3)))
; DI int lane_id_() { int l; asm volatile("v_mbcnt_lo_u32_b32 %0, -1, 0\n\tv_mbcnt_hi_u32_b32 %0, -1, %0" : "=v"(l)); return l; }
; DI void nsa_attn_phase(int wv, const P& p_, LAS unsigned char* lds) {
;   P p = p_; { size_t z_ = 0; asm volatile("" : "+s"(z_)); p.ws = p_.ws + z_; }
;   const bf16_t* hb = (const bf16_t*)(p.ws + WS_BIG); const int ld = 2816;
;   bf16_t* ob = (bf16_t*)(p.ws + WS_O);
;   LAS bf16_t* KsB[2] = {(LAS bf16_t*)lds, (LAS bf16_t*)(lds + 17920)}; LAS bf16_t* VtB[2] = {(LAS bf16_t*)(lds + 9216), (LAS bf16_t*)(lds + 17920 + 9216)};
;   LAS bf16_t* KC = (LAS bf16_t*)(lds + 35840); LAS bf16_t* VCT = (LAS bf16_t*)(lds + 72704);
;   LAS float* OUTL = (LAS float*)(lds + 35840);
;   LAS float* G4s = (LAS float*)(lds + 105984); LAS float* Lsm = (LAS float*)(lds + 122368); LAS float* BT = (LAS float*)(lds + 138752);
;   LAS unsigned* SELM = (LAS unsigned*)(lds + 140864); LAS unsigned* UNI = (LAS unsigned*)(lds + 141376);
;   for (int it = blockIdx.x; it < 2048; it += gridDim.x) {
;     int tid_ = wv * 64 + lane_id_(); asm volatile("" : "+v"(tid_)); const int tid = tid_, wid = wv, lane = tid & 63, r = lane & 31, h = lane >> 5, tl = r >> 2, hd = r & 3;
;     const int c = it & 255, ii = it >> 8, bg = c >> 3, b = bg >> 2, g = bg & 3, j8 = c & 7;
;     const int qi = (ii & 1) ? (16 * (ii >> 1) + 15 - j8) : (16 * (ii >> 1) + j8);
;     const int t0 = 64 * qi, tw = t0 + 8 * wid, t = tw + tl, head = g * 4 + hd;
;     const int nct = (4 * qi + 2) / 64 + 1;
.LBB0_657:
	v_readlane_b32 s4, v253, 12
	v_readlane_b32 s5, v253, 13
	s_mov_b64 s[0:1], 0
	s_andn2_b64 vcc, exec, s[4:5]
	s_cbranch_vccnz .LBB0_601
	v_readlane_b32 s8, v254, 27
	v_readlane_b32 s22, v254, 41
	v_readlane_b32 s23, v254, 42
	s_add_u32 s6, s22, s0
	s_addc_u32 s7, s23, s1
	s_add_u32 s82, s6, 0x7000000
	s_addc_u32 s83, s7, 0
	s_add_u32 s62, s6, 0x1b000000
	s_addc_u32 s63, s7, 0
	s_add_u32 s54, s6, 0x1f440000
	s_addc_u32 s51, s7, 0
	s_add_u32 s33, s6, 0x1f540000
	s_addc_u32 s49, s7, 0
	s_add_u32 s28, s6, 0x2c27800
	s_addc_u32 s29, s7, 0
	v_readlane_b32 s4, v254, 6
	s_add_u32 s46, s4, s0
	v_readlane_b32 s0, v254, 7
	s_addc_u32 s47, s0, s1
	v_readlane_b32 s0, v252, 14
	s_and_b32 s94, s0, 7
	s_lshl_b32 s94, s94, 5
	s_lshr_b32 s4, s0, 3
	s_or_b32 s94, s94, s4
	s_cmpk_eq_u32 s68, 0x100
	s_cselect_b32 s94, s94, s0
	s_cmpk_lt_u32 s69, 0x100
	s_cbranch_scc1 .Lnsa_prio_skip
	s_setprio 2
